# GEMM and gMLP accumulator zeroing between tiles with v_mov_b64 (half the moves)
# speedup vs baseline: 1.0141x; 1.0014x over previous
; template <class Epi, class Sched, bool ALIGN_EPI = false, bool SP2 = false>
; __device__ __forceinline__ void gemm_phase(PG8_LAS unsigned char* lds, const Gemm g, const Sched& S, const Epi& E) {
;     ...
; #pragma unroll
;         for (int a = 0; a < 2; ++a)
; #pragma unroll
;             for (int b = 0; b < 2; ++b)
; #pragma unroll
;                 for (int m = 0; m < 4; ++m)
; #pragma unroll
;                     for (int n = 0; n < 2; ++n) acc[a][b][m][n] = (f32x4){0.f, 0.f, 0.f, 0.f};
;         cur = nxt; cA = nA; cB = nB; ++ui;
.LBB0_61:
	s_add_u32 s56, s56, 0x80
	s_addc_u32 s57, s57, 0
	s_add_u32 s38, s58, 0x100
	v_mov_b32_e32 v0, 0
	s_addc_u32 s78, s59, 0
	s_mov_b32 s58, 0
	v_mov_b32_e32 v1, v0
	v_mov_b64_e32 v[2:3], 0
	v_mov_b64_e32 v[4:5], 0
	v_mov_b64_e32 v[6:7], 0
	v_mov_b64_e32 v[16:17], 0
	v_mov_b64_e32 v[18:19], 0
	v_mov_b64_e32 v[20:21], 0
	v_mov_b64_e32 v[22:23], 0
	v_mov_b64_e32 v[32:33], 0
	v_mov_b64_e32 v[34:35], 0
	v_mov_b64_e32 v[36:37], 0
	v_mov_b64_e32 v[38:39], 0
	v_mov_b64_e32 v[48:49], 0
	v_mov_b64_e32 v[50:51], 0
	v_mov_b64_e32 v[52:53], 0
	v_mov_b64_e32 v[54:55], 0
	v_mov_b64_e32 v[8:9], 0
	v_mov_b64_e32 v[10:11], 0
	v_mov_b64_e32 v[12:13], 0
	v_mov_b64_e32 v[14:15], 0
	v_mov_b64_e32 v[24:25], 0
	v_mov_b64_e32 v[26:27], 0
	v_mov_b64_e32 v[28:29], 0
	v_mov_b64_e32 v[30:31], 0
	v_mov_b64_e32 v[40:41], 0
	v_mov_b64_e32 v[42:43], 0
	v_mov_b64_e32 v[44:45], 0
	v_mov_b64_e32 v[46:47], 0
	v_mov_b64_e32 v[56:57], 0
	v_mov_b64_e32 v[58:59], 0
	v_mov_b64_e32 v[60:61], 0
	v_mov_b64_e32 v[62:63], 0
	v_mov_b64_e32 v[80:81], 0
	v_mov_b64_e32 v[82:83], 0
	v_mov_b64_e32 v[84:85], 0
	v_mov_b64_e32 v[86:87], 0
	s_waitcnt vmcnt(0)
	v_mov_b64_e32 v[96:97], 0
	v_mov_b64_e32 v[98:99], 0
	v_mov_b64_e32 v[100:101], 0
	v_mov_b64_e32 v[102:103], 0
	v_mov_b64_e32 v[112:113], 0
	v_mov_b64_e32 v[114:115], 0
	v_mov_b64_e32 v[116:117], 0
	v_mov_b64_e32 v[118:119], 0
	v_mov_b64_e32 v[128:129], 0
	v_mov_b64_e32 v[130:131], 0
	v_mov_b64_e32 v[132:133], 0
	v_mov_b64_e32 v[134:135], 0
	v_mov_b64_e32 v[88:89], 0
	v_mov_b64_e32 v[90:91], 0
	v_mov_b64_e32 v[92:93], 0
	v_mov_b64_e32 v[94:95], 0
	v_mov_b64_e32 v[104:105], 0
	v_mov_b64_e32 v[106:107], 0
	v_mov_b64_e32 v[108:109], 0
	v_mov_b64_e32 v[110:111], 0
	v_mov_b64_e32 v[120:121], 0
	v_mov_b64_e32 v[122:123], 0
	v_mov_b64_e32 v[124:125], 0
	v_mov_b64_e32 v[126:127], 0
	v_mov_b64_e32 v[136:137], 0
	v_mov_b64_e32 v[138:139], 0
	v_mov_b64_e32 v[140:141], 0
	v_mov_b64_e32 v[142:143], 0

; template <class Epi, class Sched, bool ALIGN_EPI = false, bool SP2 = false>
; __device__ __forceinline__ void gemm_phase(PG8_LAS unsigned char* lds, const Gemm g, const Sched& S, const Epi& E) {
;     ...
;         const bool has_next = S.next(ui + 1, nxt);
;         const char* nA = has_next ? (const char*)g.A + S.a_byte(nxt, K) : cA; const char* nB = has_next ? (const char*)g.Bt + (size_t)nxt.pn * tstep : cB;
;     ...
; #pragma unroll
;         for (int a = 0; a < 2; ++a)
; #pragma unroll
;             for (int b = 0; b < 2; ++b)
; #pragma unroll
;                 for (int m = 0; m < 4; ++m)
; #pragma unroll
;                     for (int n = 0; n < 2; ++n) acc[a][b][m][n] = (f32x4){0.f, 0.f, 0.f, 0.f};
;         cur = nxt; cA = nA; cB = nB; ++ui;
.LBB0_137:
	s_ashr_i32 s41, s40, 31
	s_lshl_b64 s[44:45], s[40:41], 19
	s_add_u32 s44, s12, s44
	s_addc_u32 s45, s13, s45
	s_and_b64 s[46:47], s[4:5], exec
	s_cselect_b32 s41, s45, s51
	s_cselect_b32 s49, s44, s50
	s_ashr_i32 s21, s20, 31
	s_lshl_b64 s[46:47], s[20:21], 19
	s_add_u32 s46, s31, s46
	s_addc_u32 s47, s35, s47
	s_and_b64 s[54:55], s[4:5], exec
	s_cselect_b32 s21, s47, s53
	s_cselect_b32 s65, s46, s52
	s_add_u32 s50, s50, 0x40080
	s_addc_u32 s51, s51, 0
	s_add_u32 s66, s52, 0x100
	v_mov_b32_e32 v0, 0
	s_addc_u32 s67, s53, 0
	s_mov_b32 s68, -2
	v_mov_b32_e32 v1, v0
	v_mov_b64_e32 v[2:3], 0
	v_mov_b64_e32 v[4:5], 0
	v_mov_b64_e32 v[6:7], 0
	v_mov_b64_e32 v[12:13], 0
	v_mov_b64_e32 v[14:15], 0
	v_mov_b64_e32 v[20:21], 0
	v_mov_b64_e32 v[22:23], 0
	v_mov_b64_e32 v[28:29], 0
	v_mov_b64_e32 v[30:31], 0
	v_mov_b64_e32 v[36:37], 0
	v_mov_b64_e32 v[38:39], 0
	v_mov_b64_e32 v[44:45], 0
	v_mov_b64_e32 v[46:47], 0
	v_mov_b64_e32 v[52:53], 0
	v_mov_b64_e32 v[54:55], 0
	v_mov_b64_e32 v[8:9], 0
	v_mov_b64_e32 v[10:11], 0
	v_mov_b64_e32 v[16:17], 0
	v_mov_b64_e32 v[18:19], 0
	v_mov_b64_e32 v[24:25], 0
	v_mov_b64_e32 v[26:27], 0
	v_mov_b64_e32 v[32:33], 0
	v_mov_b64_e32 v[34:35], 0
	v_mov_b64_e32 v[40:41], 0
	v_mov_b64_e32 v[42:43], 0
	v_mov_b64_e32 v[48:49], 0
	v_mov_b64_e32 v[50:51], 0
	v_mov_b64_e32 v[56:57], 0
	v_mov_b64_e32 v[58:59], 0
	v_mov_b64_e32 v[60:61], 0
	v_mov_b64_e32 v[62:63], 0
	s_waitcnt vmcnt(0)
	v_mov_b64_e32 v[64:65], 0
	v_mov_b64_e32 v[66:67], 0
	v_mov_b64_e32 v[68:69], 0
	v_mov_b64_e32 v[70:71], 0
	v_mov_b64_e32 v[72:73], 0
	v_mov_b64_e32 v[74:75], 0
	v_mov_b64_e32 v[76:77], 0
	v_mov_b64_e32 v[78:79], 0
	v_mov_b64_e32 v[88:89], 0
	v_mov_b64_e32 v[90:91], 0
	v_mov_b64_e32 v[100:101], 0
	v_mov_b64_e32 v[102:103], 0
	v_mov_b64_e32 v[104:105], 0
	v_mov_b64_e32 v[106:107], 0
	v_mov_b64_e32 v[108:109], 0
	v_mov_b64_e32 v[110:111], 0
	v_mov_b64_e32 v[80:81], 0
	v_mov_b64_e32 v[82:83], 0
	v_mov_b64_e32 v[84:85], 0
	v_mov_b64_e32 v[86:87], 0
	v_mov_b64_e32 v[92:93], 0
	v_mov_b64_e32 v[94:95], 0
	v_mov_b64_e32 v[96:97], 0
	v_mov_b64_e32 v[98:99], 0
	v_mov_b64_e32 v[112:113], 0
	v_mov_b64_e32 v[114:115], 0
	v_mov_b64_e32 v[116:117], 0
	v_mov_b64_e32 v[118:119], 0
	v_mov_b64_e32 v[120:121], 0
	v_mov_b64_e32 v[122:123], 0
	v_mov_b64_e32 v[124:125], 0
	v_mov_b64_e32 v[126:127], 0

; template <class Epi, class Sched, bool ALIGN_EPI = false, bool SP2 = false>
; __device__ __forceinline__ void gemm_phase(PG8_LAS unsigned char* lds, const Gemm g, const Sched& S, const Epi& E) {
;     ...
;         const bool has_next = S.next(ui + 1, nxt);
;         const char* nA = has_next ? (const char*)g.A + S.a_byte(nxt, K) : cA; const char* nB = has_next ? (const char*)g.Bt + (size_t)nxt.pn * tstep : cB;
;     ...
; #pragma unroll
;         for (int a = 0; a < 2; ++a)
; #pragma unroll
;             for (int b = 0; b < 2; ++b)
; #pragma unroll
;                 for (int m = 0; m < 4; ++m)
; #pragma unroll
;                     for (int n = 0; n < 2; ++n) acc[a][b][m][n] = (f32x4){0.f, 0.f, 0.f, 0.f};
;         cur = nxt; cA = nA; cB = nB; ++ui;
.LBB0_161:
	s_ashr_i32 s21, s20, 31
	s_lshl_b64 s[40:41], s[20:21], 19
	s_add_u32 s40, s1, s40
	v_readlane_b32 s9, v254, 39
	s_addc_u32 s41, s9, s41
	s_and_b64 s[44:45], s[4:5], exec
	s_cselect_b32 s21, s41, s49
	s_cselect_b32 s47, s40, s48
	s_ashr_i32 s9, s8, 31
	s_lshl_b64 s[44:45], s[8:9], 19
	s_add_u32 s44, s31, s44
	s_addc_u32 s45, s35, s45
	s_and_b64 s[52:53], s[4:5], exec
	s_cselect_b32 s9, s45, s51
	s_cselect_b32 s63, s44, s50
	s_add_u32 s48, s48, 0x40080
	s_addc_u32 s49, s49, 0
	s_add_u32 s64, s50, 0x100
	v_mov_b32_e32 v0, 0
	s_addc_u32 s65, s51, 0
	s_mov_b32 s66, -2
	v_mov_b32_e32 v1, v0
	v_mov_b64_e32 v[2:3], 0
	v_mov_b64_e32 v[4:5], 0
	v_mov_b64_e32 v[6:7], 0
	v_mov_b64_e32 v[16:17], 0
	v_mov_b64_e32 v[18:19], 0
	v_mov_b64_e32 v[20:21], 0
	v_mov_b64_e32 v[22:23], 0
	v_mov_b64_e32 v[32:33], 0
	v_mov_b64_e32 v[34:35], 0
	v_mov_b64_e32 v[36:37], 0
	v_mov_b64_e32 v[38:39], 0
	v_mov_b64_e32 v[48:49], 0
	v_mov_b64_e32 v[50:51], 0
	v_mov_b64_e32 v[52:53], 0
	v_mov_b64_e32 v[54:55], 0
	v_mov_b64_e32 v[8:9], 0
	v_mov_b64_e32 v[10:11], 0
	v_mov_b64_e32 v[12:13], 0
	v_mov_b64_e32 v[14:15], 0
	v_mov_b64_e32 v[24:25], 0
	v_mov_b64_e32 v[26:27], 0
	v_mov_b64_e32 v[28:29], 0
	v_mov_b64_e32 v[30:31], 0
	v_mov_b64_e32 v[40:41], 0
	v_mov_b64_e32 v[42:43], 0
	v_mov_b64_e32 v[44:45], 0
	v_mov_b64_e32 v[46:47], 0
	v_mov_b64_e32 v[56:57], 0
	v_mov_b64_e32 v[58:59], 0
	v_mov_b64_e32 v[60:61], 0
	v_mov_b64_e32 v[62:63], 0
	s_waitcnt vmcnt(0)
	v_mov_b64_e32 v[64:65], 0
	v_mov_b64_e32 v[66:67], 0
	v_mov_b64_e32 v[68:69], 0
	v_mov_b64_e32 v[70:71], 0
	v_mov_b64_e32 v[80:81], 0
	v_mov_b64_e32 v[82:83], 0
	v_mov_b64_e32 v[84:85], 0
	v_mov_b64_e32 v[86:87], 0
	v_mov_b64_e32 v[96:97], 0
	v_mov_b64_e32 v[98:99], 0
	v_mov_b64_e32 v[100:101], 0
	v_mov_b64_e32 v[102:103], 0
	v_mov_b64_e32 v[112:113], 0
	v_mov_b64_e32 v[114:115], 0
	v_mov_b64_e32 v[116:117], 0
	v_mov_b64_e32 v[118:119], 0
	v_mov_b64_e32 v[72:73], 0
	v_mov_b64_e32 v[74:75], 0
	v_mov_b64_e32 v[76:77], 0
	v_mov_b64_e32 v[78:79], 0
	v_mov_b64_e32 v[88:89], 0
	v_mov_b64_e32 v[90:91], 0
	v_mov_b64_e32 v[92:93], 0
	v_mov_b64_e32 v[94:95], 0
	v_mov_b64_e32 v[104:105], 0
	v_mov_b64_e32 v[106:107], 0
	v_mov_b64_e32 v[108:109], 0
	v_mov_b64_e32 v[110:111], 0
	v_mov_b64_e32 v[120:121], 0
	v_mov_b64_e32 v[122:123], 0
	v_mov_b64_e32 v[124:125], 0
	v_mov_b64_e32 v[126:127], 0

; template <class Epi, class Sched, bool ALIGN_EPI = false, bool SP2 = false>
; __device__ __forceinline__ void gemm_phase(PG8_LAS unsigned char* lds, const Gemm g, const Sched& S, const Epi& E) {
;     ...
;         const bool has_next = S.next(ui + 1, nxt);
;         const char* nA = has_next ? (const char*)g.A + S.a_byte(nxt, K) : cA; const char* nB = has_next ? (const char*)g.Bt + (size_t)nxt.pn * tstep : cB;
;     ...
; #pragma unroll
;         for (int a = 0; a < 2; ++a)
; #pragma unroll
;             for (int b = 0; b < 2; ++b)
; #pragma unroll
;                 for (int m = 0; m < 4; ++m)
; #pragma unroll
;                     for (int n = 0; n < 2; ++n) acc[a][b][m][n] = (f32x4){0.f, 0.f, 0.f, 0.f};
;         cur = nxt; cA = nA; cB = nB; ++ui;
.LBB0_189:
	s_ashr_i32 s11, s10, 31
	s_lshl_b64 s[20:21], s[10:11], 19
	s_add_u32 s20, s36, s20
	s_addc_u32 s21, s37, s21
	s_and_b64 s[44:45], s[40:41], exec
	s_cselect_b32 s11, s21, s49
	s_cselect_b32 s35, s20, s48
	s_ashr_i32 s9, s8, 31
	s_lshl_b64 s[44:45], s[8:9], 19
	s_add_u32 s44, s54, s44
	s_addc_u32 s45, s55, s45
	s_and_b64 s[52:53], s[40:41], exec
	s_cselect_b32 s9, s45, s51
	s_cselect_b32 s38, s44, s50
	s_add_u32 s48, s48, 0x40080
	s_addc_u32 s49, s49, 0
	s_add_u32 s47, s50, 0x100
	v_mov_b32_e32 v0, 0
	s_addc_u32 s65, s51, 0
	s_mov_b32 s66, -2
	v_mov_b32_e32 v1, v0
	v_mov_b64_e32 v[2:3], 0
	v_mov_b64_e32 v[4:5], 0
	v_mov_b64_e32 v[6:7], 0
	v_mov_b64_e32 v[16:17], 0
	v_mov_b64_e32 v[18:19], 0
	v_mov_b64_e32 v[20:21], 0
	v_mov_b64_e32 v[22:23], 0
	v_mov_b64_e32 v[32:33], 0
	v_mov_b64_e32 v[34:35], 0
	v_mov_b64_e32 v[36:37], 0
	v_mov_b64_e32 v[38:39], 0
	v_mov_b64_e32 v[48:49], 0
	v_mov_b64_e32 v[50:51], 0
	v_mov_b64_e32 v[52:53], 0
	v_mov_b64_e32 v[54:55], 0
	v_mov_b64_e32 v[8:9], 0
	v_mov_b64_e32 v[10:11], 0
	v_mov_b64_e32 v[12:13], 0
	v_mov_b64_e32 v[14:15], 0
	v_mov_b64_e32 v[24:25], 0
	v_mov_b64_e32 v[26:27], 0
	v_mov_b64_e32 v[28:29], 0
	v_mov_b64_e32 v[30:31], 0
	v_mov_b64_e32 v[40:41], 0
	v_mov_b64_e32 v[42:43], 0
	v_mov_b64_e32 v[44:45], 0
	v_mov_b64_e32 v[46:47], 0
	v_mov_b64_e32 v[56:57], 0
	v_mov_b64_e32 v[58:59], 0
	v_mov_b64_e32 v[60:61], 0
	v_mov_b64_e32 v[62:63], 0
	s_waitcnt vmcnt(0)
	v_mov_b64_e32 v[64:65], 0
	v_mov_b64_e32 v[66:67], 0
	v_mov_b64_e32 v[68:69], 0
	v_mov_b64_e32 v[70:71], 0
	v_mov_b64_e32 v[80:81], 0
	v_mov_b64_e32 v[82:83], 0
	v_mov_b64_e32 v[84:85], 0
	v_mov_b64_e32 v[86:87], 0
	v_mov_b64_e32 v[96:97], 0
	v_mov_b64_e32 v[98:99], 0
	v_mov_b64_e32 v[100:101], 0
	v_mov_b64_e32 v[102:103], 0
	v_mov_b64_e32 v[112:113], 0
	v_mov_b64_e32 v[114:115], 0
	v_mov_b64_e32 v[116:117], 0
	v_mov_b64_e32 v[118:119], 0
	v_mov_b64_e32 v[72:73], 0
	v_mov_b64_e32 v[74:75], 0
	v_mov_b64_e32 v[76:77], 0
	v_mov_b64_e32 v[78:79], 0
	v_mov_b64_e32 v[88:89], 0
	v_mov_b64_e32 v[90:91], 0
	v_mov_b64_e32 v[92:93], 0
	v_mov_b64_e32 v[94:95], 0
	v_mov_b64_e32 v[104:105], 0
	v_mov_b64_e32 v[106:107], 0
	v_mov_b64_e32 v[108:109], 0
	v_mov_b64_e32 v[110:111], 0
	v_mov_b64_e32 v[120:121], 0
	v_mov_b64_e32 v[122:123], 0
	v_mov_b64_e32 v[124:125], 0
	v_mov_b64_e32 v[126:127], 0

; __device__ __forceinline__ void gmlp_phase(LAS unsigned char* lds, int vcu, int G, const bf16* V, bf16* U, const float* vss, const float* gv, const float* wsl, const float* bl, int tid) {
;     ...
;         f32x16 acc0 = {}, acc1 = {};
;         const int nks = 2 * (ib + 1);
;         for (int ks = 0; ks < nks; ++ks) {
.LBB0_207:
	v_mov_b32_e32 v15, 0
	v_mov_b32_e32 v14, v15
	v_mov_b32_e32 v13, v15
	v_mov_b32_e32 v12, v15
	v_mov_b32_e32 v11, v15
	v_mov_b32_e32 v10, v15
	v_mov_b32_e32 v9, v15
	v_mov_b32_e32 v8, v15
	v_mov_b32_e32 v7, v15
	v_mov_b32_e32 v6, v15
	v_mov_b32_e32 v5, v15
	v_mov_b32_e32 v4, v15
	v_mov_b32_e32 v3, v15
	v_mov_b32_e32 v2, v15
	v_mov_b32_e32 v1, v15
	v_mov_b32_e32 v0, v15
	v_mov_b32_e32 v31, v15
	v_mov_b32_e32 v30, v15
	v_mov_b32_e32 v29, v15
	v_mov_b32_e32 v28, v15
	v_mov_b32_e32 v27, v15
	v_mov_b32_e32 v26, v15
	v_mov_b32_e32 v25, v15
	v_mov_b32_e32 v24, v15
	v_mov_b32_e32 v23, v15
	v_mov_b32_e32 v22, v15
	v_mov_b32_e32 v21, v15
	v_mov_b32_e32 v20, v15
	v_mov_b32_e32 v19, v15
	v_mov_b32_e32 v18, v15
	v_mov_b32_e32 v17, v15
	v_mov_b32_e32 v16, v15
	s_and_saveexec_b64 s[48:49], s[40:41]
	s_cbranch_execz .LBB0_202
	v_mov_b32_e32 v0, 0
	s_mov_b64 s[50:51], 0
	v_mov_b32_e32 v136, v167
	v_mov_b32_e32 v137, v166
	v_mov_b32_e32 v138, v165
	v_mov_b32_e32 v1, v0
	v_mov_b64_e32 v[2:3], 0
	v_mov_b64_e32 v[4:5], 0
	v_mov_b64_e32 v[6:7], 0
	v_mov_b64_e32 v[8:9], 0
	v_mov_b64_e32 v[10:11], 0
	v_mov_b64_e32 v[12:13], 0
	v_mov_b64_e32 v[14:15], 0
	v_mov_b64_e32 v[16:17], 0
	v_mov_b64_e32 v[18:19], 0
	v_mov_b64_e32 v[20:21], 0
	v_mov_b64_e32 v[22:23], 0
	v_mov_b64_e32 v[24:25], 0
	v_mov_b64_e32 v[26:27], 0
	v_mov_b64_e32 v[28:29], 0
	v_mov_b64_e32 v[30:31], 0

; template <class Epi, class Sched, bool ALIGN_EPI = false, bool SP2 = false>
; __device__ __forceinline__ void gemm_phase(PG8_LAS unsigned char* lds, const Gemm g, const Sched& S, const Epi& E) {
;     ...
;         const bool has_next = S.next(ui + 1, nxt);
;         const char* nA = has_next ? (const char*)g.A + S.a_byte(nxt, K) : cA; const char* nB = has_next ? (const char*)g.Bt + (size_t)nxt.pn * tstep : cB;
;     ...
; #pragma unroll
;         for (int a = 0; a < 2; ++a)
; #pragma unroll
;             for (int b = 0; b < 2; ++b)
; #pragma unroll
;                 for (int m = 0; m < 4; ++m)
; #pragma unroll
;                     for (int n = 0; n < 2; ++n) acc[a][b][m][n] = (f32x4){0.f, 0.f, 0.f, 0.f};
;         cur = nxt; cA = nA; cB = nB; ++ui;
.LBB0_287:
	s_ashr_i32 s71, s70, 31
	s_lshl_b64 s[6:7], s[70:71], 19
	s_add_u32 s74, s16, s6
	s_addc_u32 s75, s84, s7
	s_and_b64 s[4:5], s[4:5], exec
	s_cselect_b32 s9, s75, s77
	s_cselect_b32 s71, s74, s76
	s_add_u32 s4, s78, 0x40080
	s_addc_u32 s5, s79, 0
	s_add_u32 s78, s76, 0x100
	v_mov_b32_e32 v0, 0
	s_addc_u32 s79, s77, 0
	s_mov_b32 vcc_lo, -2
	v_mov_b32_e32 v1, v0
	v_mov_b64_e32 v[2:3], 0
	v_mov_b64_e32 v[4:5], 0
	v_mov_b64_e32 v[6:7], 0
	v_mov_b64_e32 v[16:17], 0
	v_mov_b64_e32 v[18:19], 0
	v_mov_b64_e32 v[20:21], 0
	v_mov_b64_e32 v[22:23], 0
	v_mov_b64_e32 v[32:33], 0
	v_mov_b64_e32 v[34:35], 0
	v_mov_b64_e32 v[36:37], 0
	v_mov_b64_e32 v[38:39], 0
	v_mov_b64_e32 v[48:49], 0
	v_mov_b64_e32 v[50:51], 0
	v_mov_b64_e32 v[52:53], 0
	v_mov_b64_e32 v[54:55], 0
	v_mov_b64_e32 v[8:9], 0
	v_mov_b64_e32 v[10:11], 0
	v_mov_b64_e32 v[12:13], 0
	v_mov_b64_e32 v[14:15], 0
	v_mov_b64_e32 v[24:25], 0
	v_mov_b64_e32 v[26:27], 0
	v_mov_b64_e32 v[28:29], 0
	v_mov_b64_e32 v[30:31], 0
	v_mov_b64_e32 v[40:41], 0
	v_mov_b64_e32 v[42:43], 0
	v_mov_b64_e32 v[44:45], 0
	v_mov_b64_e32 v[46:47], 0
	v_mov_b64_e32 v[56:57], 0
	v_mov_b64_e32 v[58:59], 0
	v_mov_b64_e32 v[60:61], 0
	v_mov_b64_e32 v[62:63], 0
	v_mov_b64_e32 v[80:81], 0
	v_mov_b64_e32 v[82:83], 0
	v_mov_b64_e32 v[84:85], 0
	v_mov_b64_e32 v[86:87], 0
	v_mov_b64_e32 v[112:113], 0
	v_mov_b64_e32 v[114:115], 0
	v_mov_b64_e32 v[116:117], 0
	v_mov_b64_e32 v[118:119], 0
	v_mov_b64_e32 v[128:129], 0
	v_mov_b64_e32 v[130:131], 0
	v_mov_b64_e32 v[132:133], 0
	v_mov_b64_e32 v[134:135], 0
	v_mov_b64_e32 v[144:145], 0
	v_mov_b64_e32 v[146:147], 0
	v_mov_b64_e32 v[148:149], 0
	v_mov_b64_e32 v[150:151], 0
	v_mov_b64_e32 v[104:105], 0
	v_mov_b64_e32 v[106:107], 0
	v_mov_b64_e32 v[108:109], 0
	v_mov_b64_e32 v[110:111], 0
	v_mov_b64_e32 v[120:121], 0
	v_mov_b64_e32 v[122:123], 0
	v_mov_b64_e32 v[124:125], 0
	v_mov_b64_e32 v[126:127], 0
	v_mov_b64_e32 v[136:137], 0
	v_mov_b64_e32 v[138:139], 0
	v_mov_b64_e32 v[140:141], 0
	v_mov_b64_e32 v[142:143], 0
	v_mov_b64_e32 v[152:153], 0
	v_mov_b64_e32 v[154:155], 0
	v_mov_b64_e32 v[156:157], 0
	v_mov_b64_e32 v[158:159], 0

; template <class Epi, class Sched, bool ALIGN_EPI = false, bool SP2 = false>
; __device__ __forceinline__ void gemm_phase(PG8_LAS unsigned char* lds, const Gemm g, const Sched& S, const Epi& E) {
;     ...
;         const bool has_next = S.next(ui + 1, nxt);
;         const char* nA = has_next ? (const char*)g.A + S.a_byte(nxt, K) : cA; const char* nB = has_next ? (const char*)g.Bt + (size_t)nxt.pn * tstep : cB;
;     ...
; #pragma unroll
;         for (int a = 0; a < 2; ++a)
; #pragma unroll
;             for (int b = 0; b < 2; ++b)
; #pragma unroll
;                 for (int m = 0; m < 4; ++m)
; #pragma unroll
;                     for (int n = 0; n < 2; ++n) acc[a][b][m][n] = (f32x4){0.f, 0.f, 0.f, 0.f};
;         cur = nxt; cA = nA; cB = nB; ++ui;
.LBB0_333:
	s_ashr_i32 s47, s46, 31
	s_lshl_b64 s[48:49], s[46:47], 19
	s_add_u32 s48, s36, s48
	s_addc_u32 s49, s37, s49
	s_and_b64 s[50:51], s[42:43], exec
	s_cselect_b32 s5, s49, s7
	s_cselect_b32 s16, s48, s6
	s_ashr_i32 s45, s44, 31
	s_lshl_b64 s[50:51], s[44:45], 19
	s_add_u32 s50, s1, s50
	s_addc_u32 s51, s66, s51
	s_and_b64 s[52:53], s[42:43], exec
	s_cselect_b32 s38, s51, s9
	s_cselect_b32 s45, s50, s8
	s_add_u32 s6, s6, 0x40080
	s_addc_u32 s7, s7, 0
	s_add_u32 s47, s8, 0x100
	v_mov_b32_e32 v0, 0
	s_addc_u32 s62, s9, 0
	s_mov_b32 s63, -2
	v_mov_b32_e32 v1, v0
	v_mov_b64_e32 v[2:3], 0
	v_mov_b64_e32 v[4:5], 0
	v_mov_b64_e32 v[6:7], 0
	v_mov_b64_e32 v[16:17], 0
	v_mov_b64_e32 v[18:19], 0
	v_mov_b64_e32 v[20:21], 0
	v_mov_b64_e32 v[22:23], 0
	v_mov_b64_e32 v[32:33], 0
	v_mov_b64_e32 v[34:35], 0
	v_mov_b64_e32 v[36:37], 0
	v_mov_b64_e32 v[38:39], 0
	v_mov_b64_e32 v[48:49], 0
	v_mov_b64_e32 v[50:51], 0
	v_mov_b64_e32 v[52:53], 0
	v_mov_b64_e32 v[54:55], 0
	v_mov_b64_e32 v[8:9], 0
	v_mov_b64_e32 v[10:11], 0
	v_mov_b64_e32 v[12:13], 0
	v_mov_b64_e32 v[14:15], 0
	v_mov_b64_e32 v[24:25], 0
	v_mov_b64_e32 v[26:27], 0
	v_mov_b64_e32 v[28:29], 0
	v_mov_b64_e32 v[30:31], 0
	v_mov_b64_e32 v[40:41], 0
	v_mov_b64_e32 v[42:43], 0
	v_mov_b64_e32 v[44:45], 0
	v_mov_b64_e32 v[46:47], 0
	v_mov_b64_e32 v[56:57], 0
	v_mov_b64_e32 v[58:59], 0
	v_mov_b64_e32 v[60:61], 0
	v_mov_b64_e32 v[62:63], 0
	s_waitcnt vmcnt(0)
	v_mov_b64_e32 v[64:65], 0
	v_mov_b64_e32 v[66:67], 0
	v_mov_b64_e32 v[68:69], 0
	v_mov_b64_e32 v[70:71], 0
	v_mov_b64_e32 v[80:81], 0
	v_mov_b64_e32 v[82:83], 0
	v_mov_b64_e32 v[84:85], 0
	v_mov_b64_e32 v[86:87], 0
	v_mov_b64_e32 v[96:97], 0
	v_mov_b64_e32 v[98:99], 0
	v_mov_b64_e32 v[100:101], 0
	v_mov_b64_e32 v[102:103], 0
	v_mov_b64_e32 v[112:113], 0
	v_mov_b64_e32 v[114:115], 0
	v_mov_b64_e32 v[116:117], 0
	v_mov_b64_e32 v[118:119], 0
	v_mov_b64_e32 v[72:73], 0
	v_mov_b64_e32 v[74:75], 0
	v_mov_b64_e32 v[76:77], 0
	v_mov_b64_e32 v[78:79], 0
	v_mov_b64_e32 v[88:89], 0
	v_mov_b64_e32 v[90:91], 0
	v_mov_b64_e32 v[92:93], 0
	v_mov_b64_e32 v[94:95], 0
	v_mov_b64_e32 v[104:105], 0
	v_mov_b64_e32 v[106:107], 0
	v_mov_b64_e32 v[108:109], 0
	v_mov_b64_e32 v[110:111], 0
	v_mov_b64_e32 v[120:121], 0
	v_mov_b64_e32 v[122:123], 0
	v_mov_b64_e32 v[124:125], 0
	v_mov_b64_e32 v[126:127], 0
